# v26 with the phase-1 copier stop threshold at 665 tiles done
# baseline (speedup 1.0000x reference)
.Lcp1_entry:
	v_readfirstlane_b32 s0, v192
	v_lshlrev_b32_e32 v16, 4, v192
	s_add_u32 s4, s38, 0xc7b7100
	s_addc_u32 s5, s39, 0
	s_add_u32 s6, s38, 0xc7b7200
	s_addc_u32 s7, s39, 0
	s_lshr_b32 s0, s0, 6
	s_mov_b32 s1, 0
	s_mov_b32 s30, 2
	v_mov_b32_e32 v93, 0
	v_mov_b32_e32 v94, 1
	v_mov_b32_e32 v95, 16
	v_mov_b32_e32 v96, 20
	v_add_u32_e32 v17, 0x2000, v16
	v_add_u32_e32 v18, 0x4000, v16
	v_add_u32_e32 v19, 0x6000, v16
	v_add_u32_e32 v20, 0x8000, v16
	v_add_u32_e32 v21, 0xa000, v16
	v_add_u32_e32 v22, 0xc000, v16
	v_add_u32_e32 v23, 0xe000, v16
	v_add_u32_e32 v104, 0x10000, v16
	v_add_u32_e32 v105, 0x12000, v16
	v_add_u32_e32 v106, 0x14000, v16
	v_add_u32_e32 v107, 0x16000, v16
	v_add_u32_e32 v108, 0x18000, v16
	v_add_u32_e32 v109, 0x1a000, v16
	v_add_u32_e32 v110, 0x1c000, v16
	v_add_u32_e32 v111, 0x1e000, v16
	s_barrier
	s_cmp_lg_u32 s0, 0
	s_cbranch_scc1 .Lcp1_p0
	s_mov_b64 s[22:23], exec
	s_mov_b64 exec, 1
	global_load_dword v118, v93, s[6:7] sc1
	v_mov_b32_e32 v117, 0xa80
	s_waitcnt vmcnt(0)
	v_readfirstlane_b32 s25, v118
	s_cmpk_gt_u32 s25, 0x299
	s_cbranch_scc1 .Lcp1_pnone
	v_mov_b32_e32 v117, 2
	global_atomic_add v117, v93, v117, s[4:5] sc0
	s_waitcnt vmcnt(0)

.Lcp1_ac_A_j:
	s_lshl_b32 s18, s18, 17
	v_add_u32_e32 v92, s24, v16
	s_add_u32 s14, s36, s19
	s_addc_u32 s15, s37, 0
	s_add_u32 s14, s14, s18
	s_addc_u32 s15, s15, 0
	s_add_u32 s12, s12, s18
	s_addc_u32 s13, s13, 0
	s_add_u32 s12, s12, 0x2000
	s_addc_u32 s13, s13, 0
	global_load_dwordx4 v[180:183], v16, s[12:13] nt
	global_load_dwordx4 v[184:187], v17, s[12:13] nt
	global_load_dwordx4 v[188:191], v18, s[12:13] nt
	global_load_dwordx4 v[196:199], v19, s[12:13] nt
	global_load_dwordx4 v[200:203], v20, s[12:13] nt
	global_load_dwordx4 v[204:207], v21, s[12:13] nt
	global_load_dwordx4 v[208:211], v22, s[12:13] nt
	global_load_dwordx4 v[212:215], v23, s[12:13] nt
	global_load_dwordx4 v[216:219], v104, s[12:13] nt
	global_load_dwordx4 v[220:223], v105, s[12:13] nt
	global_load_dwordx4 v[224:227], v106, s[12:13] nt
	global_load_dwordx4 v[228:231], v107, s[12:13] nt
	global_load_dwordx4 v[244:247], v108, s[12:13] nt
	global_load_dwordx4 v[248:251], v109, s[12:13] nt
	global_load_dwordx4 v[4:7], v110, s[12:13] nt
	global_load_dwordx4 v[8:11], v92, s[12:13] nt
	s_waitcnt vmcnt(31)
	global_store_dwordx4 v16, v[30:33], s[10:11] nt
	s_waitcnt vmcnt(31)
	global_store_dwordx4 v17, v[34:37], s[10:11] nt
	s_waitcnt vmcnt(31)
	global_store_dwordx4 v18, v[38:41], s[10:11] nt
	s_waitcnt vmcnt(31)
	global_store_dwordx4 v19, v[42:45], s[10:11] nt
	s_waitcnt vmcnt(31)
	global_store_dwordx4 v20, v[46:49], s[10:11] nt
	s_waitcnt vmcnt(31)
	global_store_dwordx4 v21, v[50:53], s[10:11] nt
	s_waitcnt vmcnt(31)
	global_store_dwordx4 v22, v[54:57], s[10:11] nt
	s_waitcnt vmcnt(31)
	global_store_dwordx4 v23, v[58:61], s[10:11] nt
	s_waitcnt vmcnt(31)
	global_store_dwordx4 v104, v[62:65], s[10:11] nt
	s_waitcnt vmcnt(31)
	global_store_dwordx4 v105, v[66:69], s[10:11] nt
	s_waitcnt vmcnt(31)
	global_store_dwordx4 v106, v[70:73], s[10:11] nt
	s_waitcnt vmcnt(31)
	global_store_dwordx4 v107, v[74:77], s[10:11] nt
	s_waitcnt vmcnt(31)
	global_store_dwordx4 v108, v[164:167], s[10:11] nt
	s_waitcnt vmcnt(31)
	global_store_dwordx4 v109, v[168:171], s[10:11] nt
	s_waitcnt vmcnt(31)
	global_store_dwordx4 v110, v[172:175], s[10:11] nt
	s_waitcnt vmcnt(31)
	global_store_dwordx4 v91, v[176:179], s[10:11] nt
	s_cmp_lg_u32 s0, 0
	s_cbranch_scc1 .Lcp1_A_s4
	s_mov_b64 s[22:23], exec
	s_mov_b64 exec, 1
	s_cmp_lg_u32 s1, 0
	s_cbranch_scc1 .Lcp1_A_s4stop
	s_waitcnt vmcnt(32)
	v_readfirstlane_b32 s25, v118
	s_cmpk_gt_u32 s25, 0x299
	s_cselect_b32 s1, 1, 0
	v_readfirstlane_b32 s26, v117
	s_cmpk_ge_u32 s26, 0xa80
	s_cselect_b32 s27, 1, 0
	s_or_b32 s1, s1, s27
	s_branch .Lcp1_A_s4pub

.Lcp1_ac_B_j:
	s_lshl_b32 s18, s18, 17
	v_add_u32_e32 v91, s24, v16
	s_add_u32 s10, s36, s19
	s_addc_u32 s11, s37, 0
	s_add_u32 s10, s10, s18
	s_addc_u32 s11, s11, 0
	s_add_u32 s8, s8, s18
	s_addc_u32 s9, s9, 0
	s_add_u32 s8, s8, 0x2000
	s_addc_u32 s9, s9, 0
	global_load_dwordx4 v[30:33], v16, s[8:9] nt
	global_load_dwordx4 v[34:37], v17, s[8:9] nt
	global_load_dwordx4 v[38:41], v18, s[8:9] nt
	global_load_dwordx4 v[42:45], v19, s[8:9] nt
	global_load_dwordx4 v[46:49], v20, s[8:9] nt
	global_load_dwordx4 v[50:53], v21, s[8:9] nt
	global_load_dwordx4 v[54:57], v22, s[8:9] nt
	global_load_dwordx4 v[58:61], v23, s[8:9] nt
	global_load_dwordx4 v[62:65], v104, s[8:9] nt
	global_load_dwordx4 v[66:69], v105, s[8:9] nt
	global_load_dwordx4 v[70:73], v106, s[8:9] nt
	global_load_dwordx4 v[74:77], v107, s[8:9] nt
	global_load_dwordx4 v[164:167], v108, s[8:9] nt
	global_load_dwordx4 v[168:171], v109, s[8:9] nt
	global_load_dwordx4 v[172:175], v110, s[8:9] nt
	global_load_dwordx4 v[176:179], v91, s[8:9] nt
	s_waitcnt vmcnt(31)
	global_store_dwordx4 v16, v[180:183], s[14:15] nt
	s_waitcnt vmcnt(31)
	global_store_dwordx4 v17, v[184:187], s[14:15] nt
	s_waitcnt vmcnt(31)
	global_store_dwordx4 v18, v[188:191], s[14:15] nt
	s_waitcnt vmcnt(31)
	global_store_dwordx4 v19, v[196:199], s[14:15] nt
	s_waitcnt vmcnt(31)
	global_store_dwordx4 v20, v[200:203], s[14:15] nt
	s_waitcnt vmcnt(31)
	global_store_dwordx4 v21, v[204:207], s[14:15] nt
	s_waitcnt vmcnt(31)
	global_store_dwordx4 v22, v[208:211], s[14:15] nt
	s_waitcnt vmcnt(31)
	global_store_dwordx4 v23, v[212:215], s[14:15] nt
	s_waitcnt vmcnt(31)
	global_store_dwordx4 v104, v[216:219], s[14:15] nt
	s_waitcnt vmcnt(31)
	global_store_dwordx4 v105, v[220:223], s[14:15] nt
	s_waitcnt vmcnt(31)
	global_store_dwordx4 v106, v[224:227], s[14:15] nt
	s_waitcnt vmcnt(31)
	global_store_dwordx4 v107, v[228:231], s[14:15] nt
	s_waitcnt vmcnt(31)
	global_store_dwordx4 v108, v[244:247], s[14:15] nt
	s_waitcnt vmcnt(31)
	global_store_dwordx4 v109, v[248:251], s[14:15] nt
	s_waitcnt vmcnt(31)
	global_store_dwordx4 v110, v[4:7], s[14:15] nt
	s_waitcnt vmcnt(31)
	global_store_dwordx4 v92, v[8:11], s[14:15] nt
	s_cmp_lg_u32 s0, 0
	s_cbranch_scc1 .Lcp1_B_s4
	s_mov_b64 s[22:23], exec
	s_mov_b64 exec, 1
	s_cmp_lg_u32 s1, 0
	s_cbranch_scc1 .Lcp1_B_s4stop
	s_waitcnt vmcnt(32)
	v_readfirstlane_b32 s25, v118
	s_cmpk_gt_u32 s25, 0x299
	s_cselect_b32 s1, 1, 0
	v_readfirstlane_b32 s26, v117
	s_cmpk_ge_u32 s26, 0xa80
	s_cselect_b32 s27, 1, 0
	s_or_b32 s1, s1, s27
	s_branch .Lcp1_B_s4pub
